# GLA recurrence loop: counted vmcnt(13) at loop head instead of vmcnt(1)
# baseline (speedup 1.0000x reference)
; __device__ __forceinline__ void gla_item(LAS unsigned char* lds, int item, const bf16_t* KDT, const float* DEC, const bf16_t* GVT, const bf16_t* GQF, bf16_t* OG) {
;     const int tid = threadIdx.x, wid = __builtin_amdgcn_readfirstlane(tid >> 6), lane = tid & 63, fr = lane & 15, fq = lane >> 4;
;     const int vs = item & 7, h = (item >> 3) & 3, b = item >> 5;
;     const bf16_t* kdt = KDT + (size_t)((b * 4 + h) * 32) * 8192 + (size_t)(wid * 2 * 64 + lane) * 8;
;     const float* dec = DEC + (size_t)((b * 4 + h) * 32) * 128 + 16 * wid + 4 * fq;
;     const bf16_t* gvt = GVT + (size_t)item * (32 * 4 * 512) + (size_t)lane * 8;
;     const int f0 = 16 * (wid & 3), v0 = 16 * (wid >> 2);
;     const bf16_t* gq = GQF + ((size_t)((b * 4 + h) * 32) * 16 + (size_t)(wid & 3) * 4) * 512 + (size_t)lane * 8;
;     bf16_t* outp = OG + (size_t)item * (SEQ * 32) + (size_t)(f0 + fr) * 32 + v0 + 4 * fq;
;     f32x4 S[2]; S[0] = (f32x4){0.f, 0.f, 0.f, 0.f}; S[1] = S[0];
;     ...
;     GlaSet s0, s1, s2;
;     GLA_LOAD(s0, 0); GLA_LOAD(s1, 1);
; #pragma unroll 1
;     for (int c = 0; c < 30; c += 3) {
;         GLA_LOAD(s2, c + 2); GLA_STEP(s0, c);
;         GLA_LOAD(s0, c + 3); GLA_STEP(s1, c + 1);
;         GLA_LOAD(s1, c + 4); GLA_STEP(s2, c + 2);
.LBB0_982:
	s_bfe_u32 s0, s51, 0x30002
	s_lshl_b32 s53, s0, 7
	s_lshl_b32 s62, s0, 5
	s_lshl_b32 s0, s52, 2
	s_and_b32 s0, s0, 28
	s_ashr_i32 s63, s52, 6
	s_add_i32 s0, s0, s63
	s_lshl_b32 s36, s0, 3
	s_bfe_u32 s64, s52, 0x30003
	s_or_b32 s54, s36, s64
	s_lshl_b32 s36, s0, 5
	v_readfirstlane_b32 s65, v185
	s_ashr_i32 s37, s36, 31
	s_lshr_b32 s66, s65, 6
	s_lshl_b64 s[58:59], s[36:37], 14
	s_add_u32 s60, s46, s58
	v_lshl_or_b32 v96, s66, 7, v184
	s_addc_u32 s61, s47, s59
	v_lshlrev_b64 v[88:89], 4, v[96:97]
	s_ashr_i32 s55, s54, 31
	s_lshr_b32 s0, s65, 4
	v_lshl_add_u64 v[0:1], s[60:61], 0, v[88:89]
	s_lshl_b64 s[60:61], s[36:37], 9
	s_lshl_b64 s[36:37], s[54:55], 16
	s_bfe_u32 s67, s65, 0x20006
	s_and_b32 s0, s0, 0xffffff0
	s_add_u32 s58, s40, s58
	s_addc_u32 s59, s41, s59
	s_lshl_b32 s68, s67, 12
	s_add_u32 s58, s58, s68
	s_addc_u32 s59, s59, 0
	s_lshl_b32 s67, s67, 9
	s_add_u32 s60, s48, s60
	s_addc_u32 s61, s49, s61
	s_and_b32 s69, s65, 0xffffffc0
	s_add_u32 s60, s60, s69
	global_load_dwordx4 v[72:75], v[0:1], off
	global_load_dwordx4 v[52:55], v[0:1], off offset:1024
	s_addc_u32 s61, s61, 0
	s_lshl_b64 s[54:55], s[54:55], 17
	v_add_co_u32_e32 v0, vcc, s23, v0
	v_lshl_add_u64 v[2:3], v[100:101], 0, s[54:55]
	s_nop 0
	v_addc_co_u32_e32 v1, vcc, 0, v1, vcc
	s_movk_i32 s54, 0x1000
	v_mov_b32_e32 v107, v97
	global_load_dwordx4 v[80:83], v[2:3], off
	global_load_dwordx4 v[64:67], v[2:3], off offset:1024
	global_load_dwordx4 v[76:79], v[2:3], off offset:2048
	global_load_dwordx4 v[60:63], v[2:3], off offset:3072
	global_load_dwordx4 v[36:39], v106, s[58:59]
	global_load_dwordx4 v[28:31], v106, s[58:59] offset:1024
	global_load_dwordx4 v[24:27], v106, s[58:59] offset:2048
	global_load_dwordx4 v[16:19], v106, s[58:59] offset:3072
	global_load_dwordx4 v[32:35], v[0:1], off
	global_load_dwordx4 v[20:23], v[0:1], off offset:1024
	v_add_co_u32_e32 v0, vcc, s54, v2
	v_lshl_add_u64 v[4:5], s[58:59], 0, v[106:107]
	s_nop 0
	v_addc_co_u32_e32 v1, vcc, 0, v3, vcc
	v_add_co_u32_e32 v4, vcc, s23, v4
	global_load_dwordx4 v[56:59], v[0:1], off
	global_load_dwordx4 v[48:51], v[0:1], off offset:1024
	global_load_dwordx4 v[44:47], v[0:1], off offset:2048
	global_load_dwordx4 v[40:43], v[0:1], off offset:3072
	v_addc_co_u32_e32 v5, vcc, 0, v5, vcc
	global_load_dwordx4 v[12:15], v[4:5], off
	global_load_dwordx4 v[8:11], v[4:5], off offset:1024
	global_load_dwordx4 v[0:3], v[4:5], off offset:2048
	s_nop 0
	global_load_dwordx4 v[4:7], v[4:5], off offset:3072
	s_nop 0
	global_load_dwordx4 v[84:87], v130, s[60:61]
	global_load_dwordx4 v[68:71], v130, s[60:61] offset:512
	s_lshl_b32 s54, s63, 5
	s_add_i32 s54, s53, s54
	s_lshl_b32 s53, s63, 3
	s_add_i32 s62, s62, s53
	s_or_b32 s60, s62, s64
	s_ashr_i32 s55, s54, 31
	s_ashr_i32 s61, s60, 31
	s_lshr_b32 s53, s65, 3
	s_lshl_b64 s[58:59], s[54:55], 14
	s_lshl_b64 s[60:61], s[60:61], 17
	s_and_b32 s53, s53, 0x1fffffe0
	s_add_u32 s53, s53, s60
	v_or_b32_e32 v90, s0, v103
	s_addc_u32 s62, 0, s61
	s_lshl_b64 s[54:55], s[54:55], 9
	v_mul_lo_u32 v107, v90, s14
	v_or_b32_e32 v90, s58, v98
	v_or_b32_e32 v92, s67, v126
	s_add_u32 s54, s69, s54
	v_or_b32_e32 v110, s68, v90
	v_mov_b32_e32 v91, s62
	v_or_b32_e32 v90, s53, v102
	v_lshlrev_b32_e32 v96, 1, v92
	s_addc_u32 s55, 0, s55
	v_mov_b32_e32 v92, 0
	v_lshl_or_b32 v109, s66, 5, v108
	v_mov_b32_e32 v111, s59
	v_lshl_add_u64 v[112:113], v[90:91], 0, v[96:97]
	v_lshl_add_u64 v[114:115], s[54:55], 0, v[104:105]
	v_mov_b32_e32 v117, s61
	v_or_b32_e32 v116, s60, v98
	v_lshl_add_u64 v[118:119], s[58:59], 0, v[88:89]
	s_mov_b32 s54, -3
	v_mov_b32_e32 v93, v92
	v_mov_b32_e32 v94, v92
	v_mov_b32_e32 v95, v92
	v_mov_b32_e32 v88, v92
	v_mov_b32_e32 v89, v92
	v_mov_b32_e32 v90, v92
	v_mov_b32_e32 v91, v92
	s_waitcnt vmcnt(1)
.LBB0_983:
	v_lshl_add_u64 v[132:133], s[86:87], 0, v[118:119]
	s_mov_b32 s55, 0x14008000
	v_add_co_u32_e32 v136, vcc, s55, v132
	v_lshl_add_u64 v[134:135], s[86:87], 0, v[116:117]
	s_mov_b32 s58, 0x10802000
	v_addc_co_u32_e32 v137, vcc, 0, v133, vcc
	v_add_co_u32_e32 v144, vcc, s58, v134
	v_lshl_add_u64 v[124:125], s[86:87], 0, v[110:111]
	s_nop 0
	v_addc_co_u32_e32 v145, vcc, 0, v135, vcc
	v_add_co_u32_e32 v172, vcc, s33, v134
	s_mov_b32 s59, 0x6808000
	s_nop 0
	v_addc_co_u32_e32 v173, vcc, 0, v135, vcc
	v_add_co_u32_e32 v160, vcc, s59, v124
	v_lshl_add_u64 v[122:123], s[86:87], 0, v[112:113]
	s_nop 0
	v_addc_co_u32_e32 v161, vcc, 0, v125, vcc
	v_add_co_u32_e32 v174, vcc, s35, v122
	s_waitcnt vmcnt(13)
	v_pk_mul_f32 v[94:95], v[86:87], v[94:95]
	v_pk_mul_f32 v[92:93], v[84:85], v[92:93]
	v_pk_mul_f32 v[86:87], v[86:87], v[90:91]
	v_pk_mul_f32 v[84:85], v[84:85], v[88:89]
	s_mov_b32 s60, 0x1400c000
	v_addc_co_u32_e32 v175, vcc, 0, v123, vcc
	v_mfma_f32_16x16x32_bf16 v[80:83], v[72:75], v[80:83], v[92:95]
	v_lshl_add_u64 v[120:121], s[86:87], 0, v[114:115]
	s_add_i32 s53, s54, 3
	s_bitcmp1_b32 s53, 0
	v_mfma_f32_16x16x32_bf16 v[72:75], v[72:75], v[76:79], v[84:87]
	s_cselect_b32 s55, 0x2200, 0
	s_add_i32 s55, s55, 0
	v_add3_u32 v131, s55, v109, v127
	v_add_co_u32_e32 v84, vcc, s60, v132
	v_mfma_f32_16x16x32_bf16 v[64:67], v[52:55], v[64:67], v[80:83]
	s_nop 0
	v_addc_co_u32_e32 v85, vcc, 0, v133, vcc
	v_add_co_u32_e32 v86, vcc, s34, v124
	v_mfma_f32_16x16x32_bf16 v[52:55], v[52:55], v[60:63], v[72:75]
	s_nop 0
	v_addc_co_u32_e32 v87, vcc, 0, v125, vcc
	v_add_co_u32_e32 v176, vcc, s42, v132
	v_add3_u32 v180, s55, v107, v99
	s_nop 0
	v_addc_co_u32_e32 v177, vcc, 0, v133, vcc
	v_add_co_u32_e32 v178, vcc, s43, v134
	v_cvt_pk_bf16_f32 v72, v64, v65
	s_nop 0
	v_addc_co_u32_e32 v179, vcc, 0, v135, vcc
	global_load_dwordx4 v[88:91], v[136:137], off
	global_load_dwordx4 v[132:135], v[136:137], off offset:1024
	global_load_dwordx4 v[92:95], v[172:173], off offset:-4096
	s_nop 0
	global_load_dwordx4 v[136:139], v[144:145], off offset:1024
	global_load_dwordx4 v[140:143], v[144:145], off offset:2048
	s_nop 0
	global_load_dwordx4 v[144:147], v[144:145], off offset:3072
	s_nop 0
	global_load_dwordx4 v[148:151], v[160:161], off
	global_load_dwordx4 v[152:155], v[160:161], off offset:1024
	global_load_dwordx4 v[156:159], v[160:161], off offset:2048
	s_nop 0
	global_load_dwordx4 v[160:163], v[160:161], off offset:3072
	s_nop 0
	global_load_dwordx4 v[164:167], v[120:121], off offset:-512
	v_cvt_pk_bf16_f32 v73, v66, v67
	v_cvt_pk_bf16_f32 v74, v52, v53
	v_cvt_pk_bf16_f32 v75, v54, v55
	s_waitcnt vmcnt(11)
	v_pk_mul_f32 v[62:63], v[70:71], v[66:67]
	v_pk_mul_f32 v[60:61], v[68:69], v[64:65]
	v_pk_mul_f32 v[54:55], v[70:71], v[54:55]
	v_pk_mul_f32 v[52:53], v[68:69], v[52:53]
	v_mfma_f32_16x16x32_bf16 v[56:59], v[32:35], v[56:59], v[60:63]
	ds_write_b64 v131, v[72:73]
	ds_write_b64 v131, v[74:75] offset:4352
	s_waitcnt lgkmcnt(0)
	s_barrier
; __device__ __forceinline__ void gla_item(LAS unsigned char* lds, int item, const bf16_t* KDT, const float* DEC, const bf16_t* GVT, const bf16_t* GQF, bf16_t* OG) {
;     ...
;     GlaSet s0, s1, s2;
;     GLA_LOAD(s0, 0); GLA_LOAD(s1, 1);
; #pragma unroll 1
;     for (int c = 0; c < 30; c += 3) {
;         GLA_LOAD(s2, c + 2); GLA_STEP(s0, c);
;         GLA_LOAD(s0, c + 3); GLA_STEP(s1, c + 1);
;         GLA_LOAD(s1, c + 4); GLA_STEP(s2, c + 2);
	v_mfma_f32_16x16x32_bf16 v[32:35], v[32:35], v[44:47], v[52:55]
	ds_read_b128 v[44:47], v180
	s_bitcmp1_b32 s54, 0
	v_mfma_f32_16x16x32_bf16 v[68:71], v[20:23], v[48:51], v[56:59]
	s_cselect_b32 s54, 0x2200, 0
	s_add_i32 s54, s54, 0
	v_add3_u32 v76, s54, v109, v127
	v_mfma_f32_16x16x32_bf16 v[168:171], v[20:23], v[40:43], v[32:35]
	ds_read_b128 v[20:23], v180 offset:64
	v_add3_u32 v181, s54, v107, v99
	v_add_co_u32_e32 v124, vcc, s44, v124
	s_waitcnt lgkmcnt(1)
	v_mfma_f32_16x16x32_bf16 v[32:35], v[44:47], v[36:39], 0
	ds_read_b128 v[36:39], v180 offset:128
	ds_read_b128 v[40:43], v180 offset:192
	v_addc_co_u32_e32 v125, vcc, 0, v125, vcc
	s_waitcnt lgkmcnt(2)
	v_mfma_f32_16x16x32_bf16 v[20:23], v[20:23], v[28:31], v[32:35]
	v_cvt_pk_bf16_f32 v28, v68, v69
	v_cvt_pk_bf16_f32 v29, v70, v71
	v_cvt_pk_bf16_f32 v30, v168, v169
	s_waitcnt lgkmcnt(1)
	v_mfma_f32_16x16x32_bf16 v[20:23], v[36:39], v[24:27], v[20:23]
	v_cvt_pk_bf16_f32 v31, v170, v171
	ds_write_b64 v76, v[28:29]
	ds_write_b64 v76, v[30:31] offset:4352
	v_lshl_add_u64 v[110:111], v[110:111], 0, s[24:25]
	s_waitcnt lgkmcnt(2)
	v_mfma_f32_16x16x32_bf16 v[16:19], v[40:43], v[16:19], v[20:23]
	v_lshl_add_u64 v[112:113], v[112:113], 0, s[26:27]
	v_lshl_add_u64 v[114:115], v[114:115], 0, s[28:29]
	v_lshl_add_u64 v[116:117], v[116:117], 0, s[26:27]
	v_lshl_add_u64 v[118:119], v[118:119], 0, s[24:25]
	s_mov_b32 s54, s53
	s_nop 2
	v_pk_mul_f32 v[18:19], v[18:19], s[22:23] op_sel_hi:[1,0]
	v_pk_mul_f32 v[16:17], v[16:17], s[22:23] op_sel_hi:[1,0]
	s_cmp_lt_u32 s53, 27
	v_cvt_pk_bf16_f32 v16, v16, v17
	v_cvt_pk_bf16_f32 v17, v18, v19
	global_store_dwordx2 v[174:175], v[16:17], off offset:-4096
	global_load_dwordx4 v[64:67], v[172:173], off offset:1024
	global_load_dwordx4 v[76:79], v[172:173], off offset:2048
	global_load_dwordx4 v[60:63], v[172:173], off offset:3072
	global_load_dwordx4 v[52:55], v[84:85], off offset:1024
	global_load_dwordx4 v[36:39], v[86:87], off
	global_load_dwordx4 v[28:31], v[86:87], off offset:1024
	global_load_dwordx4 v[24:27], v[86:87], off offset:2048
	global_load_dwordx4 v[80:83], v[172:173], off
	global_load_dwordx4 v[16:19], v[86:87], off offset:3072
	global_load_dwordx4 v[72:75], v[84:85], off
	s_nop 0
	global_load_dwordx4 v[84:87], v[120:121], off
	s_waitcnt lgkmcnt(0)
	s_barrier
	ds_read_b128 v[20:23], v181
	ds_read_b128 v[32:35], v181 offset:64
	s_waitcnt lgkmcnt(1)
	v_mfma_f32_16x16x32_bf16 v[12:15], v[20:23], v[12:15], 0
	ds_read_b128 v[20:23], v181 offset:128
	s_waitcnt lgkmcnt(1)
	v_mfma_f32_16x16x32_bf16 v[8:11], v[32:35], v[8:11], v[12:15]
	s_nop 4
	ds_read_b128 v[12:15], v181 offset:192
	s_waitcnt lgkmcnt(1)
	v_mfma_f32_16x16x32_bf16 v[0:3], v[20:23], v[0:3], v[8:11]
	s_waitcnt lgkmcnt(0)
	v_mfma_f32_16x16x32_bf16 v[0:3], v[12:15], v[4:7], v[0:3]
	s_waitcnt vmcnt(12)
	v_pk_mul_f32 v[6:7], v[166:167], v[70:71]
	s_nop 5
	v_pk_mul_f32 v[2:3], v[2:3], s[22:23] op_sel_hi:[1,0]
	v_pk_mul_f32 v[0:1], v[0:1], s[22:23] op_sel_hi:[1,0]
	v_pk_mul_f32 v[4:5], v[164:165], v[68:69]
	v_cvt_pk_bf16_f32 v0, v0, v1
	v_cvt_pk_bf16_f32 v1, v2, v3
	global_store_dwordx2 v[174:175], v[0:1], off
	global_load_dwordx4 v[32:35], v[176:177], off
	global_load_dwordx4 v[20:23], v[176:177], off offset:1024
	global_load_dwordx4 v[56:59], v[178:179], off
	global_load_dwordx4 v[48:51], v[178:179], off offset:1024
	global_load_dwordx4 v[44:47], v[178:179], off offset:2048
	global_load_dwordx4 v[40:43], v[178:179], off offset:3072
	global_load_dwordx4 v[12:15], v[124:125], off
	global_load_dwordx4 v[8:11], v[124:125], off offset:1024
	global_load_dwordx4 v[0:3], v[124:125], off offset:2048
	v_pk_mul_f32 v[70:71], v[166:167], v[170:171]
	v_pk_mul_f32 v[68:69], v[164:165], v[168:169]
	v_mfma_f32_16x16x32_bf16 v[92:95], v[88:91], v[92:95], v[4:7]
	s_nop 2
	global_load_dwordx4 v[4:7], v[124:125], off offset:3072
	v_mfma_f32_16x16x32_bf16 v[88:91], v[88:91], v[140:143], v[68:71]
	s_nop 2
	global_load_dwordx4 v[68:71], v[120:121], off offset:512
	v_mfma_f32_16x16x32_bf16 v[92:95], v[132:135], v[136:139], v[92:95]
	v_mfma_f32_16x16x32_bf16 v[88:91], v[132:135], v[144:147], v[88:91]
	s_nop 6
	v_cvt_pk_bf16_f32 v120, v92, v93
	v_cvt_pk_bf16_f32 v121, v94, v95
	v_cvt_pk_bf16_f32 v124, v88, v89
	v_cvt_pk_bf16_f32 v125, v90, v91
	ds_write_b64 v131, v[120:121]
	ds_write_b64 v131, v[124:125] offset:4352
	s_waitcnt lgkmcnt(0)
	s_barrier
; __device__ __forceinline__ void gla_item(LAS unsigned char* lds, int item, const bf16_t* KDT, const float* DEC, const bf16_t* GVT, const bf16_t* GQF, bf16_t* OG) {
;     ...
;     GlaSet s0, s1, s2;
;     GLA_LOAD(s0, 0); GLA_LOAD(s1, 1);
; #pragma unroll 1
;     for (int c = 0; c < 30; c += 3) {
;         GLA_LOAD(s2, c + 2); GLA_STEP(s0, c);
;         GLA_LOAD(s0, c + 3); GLA_STEP(s1, c + 1);
;         GLA_LOAD(s1, c + 4); GLA_STEP(s2, c + 2);
;     }
;     GLA_STEP(s0, 30); GLA_STEP(s1, 31);
;     ...
;     __syncthreads();
	ds_read_b128 v[132:135], v180
	ds_read_b128 v[136:139], v180 offset:64
	s_waitcnt lgkmcnt(1)
	v_mfma_f32_16x16x32_bf16 v[132:135], v[132:135], v[148:151], 0
	ds_read_b128 v[140:143], v180 offset:128
	v_add_co_u32_e32 v124, vcc, 0x1e002000, v122
	s_waitcnt lgkmcnt(1)
	v_mfma_f32_16x16x32_bf16 v[132:135], v[136:139], v[152:155], v[132:135]
	ds_read_b128 v[136:139], v180 offset:192
	v_addc_co_u32_e32 v125, vcc, 0, v123, vcc
	s_waitcnt lgkmcnt(1)
	v_mfma_f32_16x16x32_bf16 v[132:135], v[140:143], v[156:159], v[132:135]
	s_waitcnt lgkmcnt(0)
	v_mfma_f32_16x16x32_bf16 v[120:123], v[136:139], v[160:163], v[132:135]
	s_nop 7
	v_pk_mul_f32 v[122:123], v[122:123], s[22:23] op_sel_hi:[1,0]
	v_pk_mul_f32 v[120:121], v[120:121], s[22:23] op_sel_hi:[1,0]
	s_nop 0
	v_cvt_pk_bf16_f32 v120, v120, v121
	v_cvt_pk_bf16_f32 v121, v122, v123
	global_store_dwordx2 v[124:125], v[120:121], off
	s_cbranch_scc1 .LBB0_983
	s_waitcnt vmcnt(13)
	v_pk_mul_f32 v[94:95], v[86:87], v[94:95]
	v_pk_mul_f32 v[92:93], v[84:85], v[92:93]
	s_lshl_b64 s[36:37], s[36:37], 1
	s_add_u32 s36, s4, s36
	v_mfma_f32_16x16x32_bf16 v[80:83], v[72:75], v[80:83], v[92:95]
	s_addc_u32 s37, s5, s37
	s_lshl_b32 s0, s0, 1
	s_add_i32 s52, s52, s15
	v_mfma_f32_16x16x32_bf16 v[64:67], v[52:55], v[64:67], v[80:83]
	s_add_i32 s51, s51, s17
	s_cmpk_gt_i32 s52, 0xff
	s_nop 1
	v_pk_mul_f32 v[82:83], v[86:87], v[90:91]
	v_pk_mul_f32 v[80:81], v[84:85], v[88:89]
	s_nop 1
	v_cvt_pk_bf16_f32 v84, v64, v65
	v_cvt_pk_bf16_f32 v85, v66, v67
	v_mfma_f32_16x16x32_bf16 v[72:75], v[72:75], v[76:79], v[80:83]
	v_mfma_f32_16x16x32_bf16 v[52:55], v[52:55], v[60:63], v[72:75]
	s_nop 1
	v_add_u32_e32 v80, v129, v109
	v_add_u32_e32 v81, v128, v107
	ds_write_b64 v80, v[84:85]
	v_mov_b32_e32 v109, v97
	s_nop 1
	v_cvt_pk_bf16_f32 v60, v52, v53
	v_cvt_pk_bf16_f32 v61, v54, v55
	ds_write_b64 v80, v[60:61] offset:4352
	s_waitcnt lgkmcnt(0)
	s_barrier
	ds_read_b128 v[60:63], v81
	ds_read_b128 v[72:75], v81 offset:64
	ds_read_b128 v[76:79], v81 offset:128
	s_waitcnt lgkmcnt(2)
	v_mfma_f32_16x16x32_bf16 v[36:39], v[60:63], v[36:39], 0
	ds_read_b128 v[60:63], v81 offset:192
	s_waitcnt lgkmcnt(2)
	v_mfma_f32_16x16x32_bf16 v[28:31], v[72:75], v[28:31], v[36:39]
	s_waitcnt lgkmcnt(1)
	v_mfma_f32_16x16x32_bf16 v[24:27], v[76:79], v[24:27], v[28:31]
	s_nop 2
	v_lshl_add_u64 v[36:37], s[36:37], 0, v[96:97]
	s_waitcnt lgkmcnt(0)
	v_mfma_f32_16x16x32_bf16 v[16:19], v[60:63], v[16:19], v[24:27]
	v_lshl_add_u64 v[28:29], v[36:37], 0, s[0:1]
	v_lshl_add_u64 v[28:29], v[28:29], 0, v[108:109]
	s_nop 0
	v_add_co_u32_e32 v26, vcc, s45, v28
	s_nop 1
	v_addc_co_u32_e32 v27, vcc, 0, v29, vcc
	s_nop 0
	v_pk_mul_f32 v[18:19], v[18:19], s[22:23] op_sel_hi:[1,0]
	v_pk_mul_f32 v[16:17], v[16:17], s[22:23] op_sel_hi:[1,0]
	v_cvt_pk_bf16_f32 v25, v18, v19
	v_cvt_pk_bf16_f32 v24, v16, v17
	s_waitcnt vmcnt(1)
	v_pk_mul_f32 v[18:19], v[70:71], v[66:67]
	v_pk_mul_f32 v[16:17], v[68:69], v[64:65]
	global_store_dwordx2 v[26:27], v[24:25], off
	v_pk_mul_f32 v[26:27], v[70:71], v[54:55]
	v_mfma_f32_16x16x32_bf16 v[16:19], v[32:35], v[56:59], v[16:19]
	v_mul_f32_e64 v24, v68, v52
	v_mul_f32_e64 v25, v69, v53
	v_mfma_f32_16x16x32_bf16 v[16:19], v[20:23], v[48:51], v[16:19]
	s_nop 0
	v_mfma_f32_16x16x32_bf16 v[24:27], v[32:35], v[44:47], v[24:27]
	s_nop 5
	v_cvt_pk_bf16_f32 v16, v16, v17
	v_cvt_pk_bf16_f32 v17, v18, v19
	ds_write_b64 v80, v[16:17] offset:8704
	v_mfma_f32_16x16x32_bf16 v[16:19], v[20:23], v[40:43], v[24:27]
	s_nop 7
	v_cvt_pk_bf16_f32 v16, v16, v17
	v_cvt_pk_bf16_f32 v17, v18, v19
	ds_write_b64 v80, v[16:17] offset:13056
	s_waitcnt lgkmcnt(0)
	s_barrier
	ds_read_b128 v[16:19], v81 offset:8704
	ds_read_b128 v[20:23], v81 offset:8768
	s_waitcnt lgkmcnt(1)
	v_mfma_f32_16x16x32_bf16 v[12:15], v[16:19], v[12:15], 0
	ds_read_b128 v[16:19], v81 offset:8832
	s_waitcnt lgkmcnt(1)
	v_mfma_f32_16x16x32_bf16 v[8:11], v[20:23], v[8:11], v[12:15]
	s_nop 4
	ds_read_b128 v[12:15], v81 offset:8896
	s_waitcnt lgkmcnt(1)
	v_mfma_f32_16x16x32_bf16 v[0:3], v[16:19], v[0:3], v[8:11]
	s_waitcnt lgkmcnt(0)
	v_mfma_f32_16x16x32_bf16 v[0:3], v[12:15], v[4:7], v[0:3]
	s_nop 7
	v_pk_mul_f32 v[2:3], v[2:3], s[22:23] op_sel_hi:[1,0]
	v_pk_mul_f32 v[0:1], v[0:1], s[22:23] op_sel_hi:[1,0]
	s_nop 0
	v_cvt_pk_bf16_f32 v0, v0, v1
	v_cvt_pk_bf16_f32 v1, v2, v3
	v_add_co_u32_e32 v2, vcc, 0x1f000, v28
	s_nop 1
	v_addc_co_u32_e32 v3, vcc, 0, v29, vcc
	global_store_dwordx2 v[2:3], v[0:1], off
	s_barrier
	s_cbranch_scc0 .LBB0_982
	s_branch .LBB0_980
